# K-loop heads of both GEMM phases aligned to 64 bytes (code placement)
# speedup vs baseline: 1.0050x; 1.0050x over previous
.LBB0_404:
	s_ashr_i32 s55, s54, 31
	s_lshl_b64 s[2:3], s[54:55], 19
	s_add_u32 s56, s60, s2
	s_addc_u32 s57, s65, s3
	s_and_b64 s[2:3], s[10:11], exec
	s_cselect_b32 s16, s57, s15
	s_cselect_b32 s17, s56, s14
	s_ashr_i32 s31, s30, 31
	s_lshl_b64 s[2:3], s[30:31], 19
	s_add_u32 s4, s66, s2
	s_addc_u32 s5, s68, s3
	s_and_b64 s[2:3], s[10:11], exec
	s_cselect_b32 s18, s5, s13
	s_cselect_b32 s19, s4, s12
	s_add_u32 s2, s14, 0x40080
	s_addc_u32 s3, s15, 0
	s_add_u32 s20, s12, 0x100
	v_mov_b32_e32 v8, 0
	s_addc_u32 s21, s13, 0
	s_mov_b32 s22, -2
	v_mov_b32_e32 v9, v8
	v_mov_b32_e32 v10, v8
	v_mov_b32_e32 v11, v8
	v_mov_b32_e32 v12, v8
	v_mov_b32_e32 v13, v8
	v_mov_b32_e32 v14, v8
	v_mov_b32_e32 v15, v8
	v_mov_b32_e32 v24, v8
	v_mov_b32_e32 v25, v8
	v_mov_b32_e32 v26, v8
	v_mov_b32_e32 v27, v8
	v_mov_b32_e32 v28, v8
	v_mov_b32_e32 v29, v8
	v_mov_b32_e32 v30, v8
	v_mov_b32_e32 v31, v8
	v_mov_b32_e32 v40, v8
	v_mov_b32_e32 v41, v8
	v_mov_b32_e32 v42, v8
	v_mov_b32_e32 v43, v8
	v_mov_b32_e32 v44, v8
	v_mov_b32_e32 v45, v8
	v_mov_b32_e32 v46, v8
	v_mov_b32_e32 v47, v8
	v_mov_b32_e32 v56, v8
	v_mov_b32_e32 v57, v8
	v_mov_b32_e32 v58, v8
	v_mov_b32_e32 v59, v8
	v_mov_b32_e32 v60, v8
	v_mov_b32_e32 v61, v8
	v_mov_b32_e32 v62, v8
	v_mov_b32_e32 v63, v8
	v_mov_b32_e32 v16, v8
	v_mov_b32_e32 v17, v8
	v_mov_b32_e32 v18, v8
	v_mov_b32_e32 v19, v8
	v_mov_b32_e32 v20, v8
	v_mov_b32_e32 v21, v8
	v_mov_b32_e32 v22, v8
	v_mov_b32_e32 v23, v8
	v_mov_b32_e32 v32, v8
	v_mov_b32_e32 v33, v8
	v_mov_b32_e32 v34, v8
	v_mov_b32_e32 v35, v8
	v_mov_b32_e32 v36, v8
	v_mov_b32_e32 v37, v8
	v_mov_b32_e32 v38, v8
	v_mov_b32_e32 v39, v8
	v_mov_b32_e32 v48, v8
	v_mov_b32_e32 v49, v8
	v_mov_b32_e32 v50, v8
	v_mov_b32_e32 v51, v8
	v_mov_b32_e32 v52, v8
	v_mov_b32_e32 v53, v8
	v_mov_b32_e32 v54, v8
	v_mov_b32_e32 v55, v8
	v_mov_b32_e32 v64, v8
	v_mov_b32_e32 v65, v8
	v_mov_b32_e32 v66, v8
	v_mov_b32_e32 v67, v8
	v_mov_b32_e32 v68, v8
	v_mov_b32_e32 v69, v8
	v_mov_b32_e32 v70, v8
	v_mov_b32_e32 v71, v8
	v_mov_b32_e32 v72, v8
	v_mov_b32_e32 v73, v8
	v_mov_b32_e32 v74, v8
	v_mov_b32_e32 v75, v8
	v_mov_b32_e32 v76, v8
	v_mov_b32_e32 v77, v8
	v_mov_b32_e32 v78, v8
	v_mov_b32_e32 v79, v8
	v_mov_b32_e32 v88, v8
	v_mov_b32_e32 v89, v8
	v_mov_b32_e32 v90, v8
	v_mov_b32_e32 v91, v8
	v_mov_b32_e32 v92, v8
	v_mov_b32_e32 v93, v8
	v_mov_b32_e32 v94, v8
	v_mov_b32_e32 v95, v8
	v_mov_b32_e32 v106, v8
	v_mov_b32_e32 v107, v8
	v_mov_b32_e32 v108, v8
	v_mov_b32_e32 v109, v8
	v_mov_b32_e32 v110, v8
	v_mov_b32_e32 v111, v8
	v_mov_b32_e32 v112, v8
	v_mov_b32_e32 v113, v8
	v_mov_b32_e32 v122, v8
	v_mov_b32_e32 v123, v8
	v_mov_b32_e32 v124, v8
	v_mov_b32_e32 v125, v8
	v_mov_b32_e32 v126, v8
	v_mov_b32_e32 v127, v8
	v_mov_b32_e32 v128, v8
	v_mov_b32_e32 v129, v8
	v_mov_b32_e32 v80, v8
	v_mov_b32_e32 v81, v8
	v_mov_b32_e32 v82, v8
	v_mov_b32_e32 v83, v8
	v_mov_b32_e32 v84, v8
	v_mov_b32_e32 v85, v8
	v_mov_b32_e32 v86, v8
	v_mov_b32_e32 v87, v8
	v_mov_b32_e32 v98, v8
	v_mov_b32_e32 v99, v8
	v_mov_b32_e32 v100, v8
	v_mov_b32_e32 v101, v8
	v_mov_b32_e32 v102, v8
	v_mov_b32_e32 v103, v8
	v_mov_b32_e32 v104, v8
	v_mov_b32_e32 v105, v8
	v_mov_b32_e32 v114, v8
	v_mov_b32_e32 v115, v8
	v_mov_b32_e32 v116, v8
	v_mov_b32_e32 v117, v8
	v_mov_b32_e32 v118, v8
	v_mov_b32_e32 v119, v8
	v_mov_b32_e32 v120, v8
	v_mov_b32_e32 v121, v8
	v_mov_b32_e32 v130, v8
	v_mov_b32_e32 v131, v8
	v_mov_b32_e32 v132, v8
	v_mov_b32_e32 v133, v8
	v_mov_b32_e32 v134, v8
	v_mov_b32_e32 v135, v8
	v_mov_b32_e32 v136, v8
	v_mov_b32_e32 v137, v8
	.p2align 6

.LBB0_749:
	s_ashr_i32 s49, s48, 31
	s_waitcnt lgkmcnt(0)
	s_lshl_b64 s[14:15], s[48:49], 19
	s_add_u32 s38, s22, s14
	s_addc_u32 s39, s23, s15
	s_and_b64 s[14:15], s[8:9], exec
	s_cselect_b32 s3, s39, s5
	s_cselect_b32 s16, s38, s4
	s_ashr_i32 s35, s34, 31
	s_lshl_b64 s[14:15], s[34:35], 19
	s_add_u32 s40, s56, s14
	s_addc_u32 s41, s57, s15
	s_and_b64 s[14:15], s[8:9], exec
	s_cselect_b32 s17, s41, s13
	s_cselect_b32 s18, s40, s12
	s_add_u32 s4, s4, 0x40080
	s_addc_u32 s5, s5, 0
	s_add_u32 s19, s12, 0x100
	v_mov_b32_e32 v8, 0
	s_addc_u32 s26, s13, 0
	s_mov_b32 s27, -2
	v_mov_b32_e32 v9, v8
	v_mov_b32_e32 v10, v8
	v_mov_b32_e32 v11, v8
	v_mov_b32_e32 v12, v8
	v_mov_b32_e32 v13, v8
	v_mov_b32_e32 v14, v8
	v_mov_b32_e32 v15, v8
	v_mov_b32_e32 v24, v8
	v_mov_b32_e32 v25, v8
	v_mov_b32_e32 v26, v8
	v_mov_b32_e32 v27, v8
	v_mov_b32_e32 v28, v8
	v_mov_b32_e32 v29, v8
	v_mov_b32_e32 v30, v8
	v_mov_b32_e32 v31, v8
	v_mov_b32_e32 v40, v8
	v_mov_b32_e32 v41, v8
	v_mov_b32_e32 v42, v8
	v_mov_b32_e32 v43, v8
	v_mov_b32_e32 v44, v8
	v_mov_b32_e32 v45, v8
	v_mov_b32_e32 v46, v8
	v_mov_b32_e32 v47, v8
	v_mov_b32_e32 v56, v8
	v_mov_b32_e32 v57, v8
	v_mov_b32_e32 v58, v8
	v_mov_b32_e32 v59, v8
	v_mov_b32_e32 v60, v8
	v_mov_b32_e32 v61, v8
	v_mov_b32_e32 v62, v8
	v_mov_b32_e32 v63, v8
	v_mov_b32_e32 v16, v8
	v_mov_b32_e32 v17, v8
	v_mov_b32_e32 v18, v8
	v_mov_b32_e32 v19, v8
	v_mov_b32_e32 v20, v8
	v_mov_b32_e32 v21, v8
	v_mov_b32_e32 v22, v8
	v_mov_b32_e32 v23, v8
	v_mov_b32_e32 v32, v8
	v_mov_b32_e32 v33, v8
	v_mov_b32_e32 v34, v8
	v_mov_b32_e32 v35, v8
	v_mov_b32_e32 v36, v8
	v_mov_b32_e32 v37, v8
	v_mov_b32_e32 v38, v8
	v_mov_b32_e32 v39, v8
	v_mov_b32_e32 v48, v8
	v_mov_b32_e32 v49, v8
	v_mov_b32_e32 v50, v8
	v_mov_b32_e32 v51, v8
	v_mov_b32_e32 v52, v8
	v_mov_b32_e32 v53, v8
	v_mov_b32_e32 v54, v8
	v_mov_b32_e32 v55, v8
	v_mov_b32_e32 v64, v8
	v_mov_b32_e32 v65, v8
	v_mov_b32_e32 v66, v8
	v_mov_b32_e32 v67, v8
	v_mov_b32_e32 v68, v8
	v_mov_b32_e32 v69, v8
	v_mov_b32_e32 v70, v8
	v_mov_b32_e32 v71, v8
	v_mov_b32_e32 v72, v8
	v_mov_b32_e32 v73, v8
	v_mov_b32_e32 v74, v8
	v_mov_b32_e32 v75, v8
	v_mov_b32_e32 v76, v8
	v_mov_b32_e32 v77, v8
	v_mov_b32_e32 v78, v8
	v_mov_b32_e32 v79, v8
	v_mov_b32_e32 v88, v8
	v_mov_b32_e32 v89, v8
	v_mov_b32_e32 v90, v8
	v_mov_b32_e32 v91, v8
	v_mov_b32_e32 v92, v8
	v_mov_b32_e32 v93, v8
	v_mov_b32_e32 v94, v8
	v_mov_b32_e32 v95, v8
	v_mov_b32_e32 v106, v8
	v_mov_b32_e32 v107, v8
	v_mov_b32_e32 v108, v8
	v_mov_b32_e32 v109, v8
	v_mov_b32_e32 v110, v8
	v_mov_b32_e32 v111, v8
	v_mov_b32_e32 v112, v8
	v_mov_b32_e32 v113, v8
	v_mov_b32_e32 v122, v8
	v_mov_b32_e32 v123, v8
	v_mov_b32_e32 v124, v8
	v_mov_b32_e32 v125, v8
	v_mov_b32_e32 v126, v8
	v_mov_b32_e32 v127, v8
	v_mov_b32_e32 v128, v8
	v_mov_b32_e32 v129, v8
	v_mov_b32_e32 v80, v8
	v_mov_b32_e32 v81, v8
	v_mov_b32_e32 v82, v8
	v_mov_b32_e32 v83, v8
	v_mov_b32_e32 v84, v8
	v_mov_b32_e32 v85, v8
	v_mov_b32_e32 v86, v8
	v_mov_b32_e32 v87, v8
	v_mov_b32_e32 v98, v8
	v_mov_b32_e32 v99, v8
	v_mov_b32_e32 v100, v8
	v_mov_b32_e32 v101, v8
	v_mov_b32_e32 v102, v8
	v_mov_b32_e32 v103, v8
	v_mov_b32_e32 v104, v8
	v_mov_b32_e32 v105, v8
	v_mov_b32_e32 v114, v8
	v_mov_b32_e32 v115, v8
	v_mov_b32_e32 v116, v8
	v_mov_b32_e32 v117, v8
	v_mov_b32_e32 v118, v8
	v_mov_b32_e32 v119, v8
	v_mov_b32_e32 v120, v8
	v_mov_b32_e32 v121, v8
	v_mov_b32_e32 v130, v8
	v_mov_b32_e32 v131, v8
	v_mov_b32_e32 v132, v8
	v_mov_b32_e32 v133, v8
	v_mov_b32_e32 v134, v8
	v_mov_b32_e32 v135, v8
	v_mov_b32_e32 v136, v8
	v_mov_b32_e32 v137, v8
	.p2align 6
